# code placement test: attention loop and all later code shifted by 4 bytes (one s_nop before the loop entry), otherwise identical to the early-K ping-pong version
# speedup vs baseline: 1.0046x; 1.0046x over previous
; #define SBAR() __builtin_amdgcn_sched_barrier(0)
; #define VMW() asm volatile("s_waitcnt vmcnt(0)" ::: "memory")
; #define SLOAD_H(Kp, Vp, k0) do { S.st_v0 = load8(ROW(Vp, k0, sr)); S.st_v1 = load8(ROW(Vp, k0, 32 + sr));              \
;                          S.st_k0 = load8(ROW(Kp, k0, sr)); S.st_k1 = load8(ROW(Kp, k0, 32 + sr)); } while (0)
; #define SWRITE_HV(bf) do { *(bf16x8*)(V_lds + (bf) * SHM_V + vst0) = S.st_v0; *(bf16x8*)(V_lds + (bf) * SHM_V + vst1) = S.st_v1; } while (0)
; #define SWRITE_H(bf) do { SWRITE_HV(bf); SWRITE_HK(bf); } while (0)
; #define MASKT(P0_, P1_) sel_mask_tile(P0_, P1_, mw.x, mw.y, hi)
; template <int KB>
; __device__ __forceinline__ void qkt(f32x16& p0, f32x16& p1, const char* K_lds, int r32, int hi, const bf16x8* qr) {
;     p0 = f32x16{}; p1 = f32x16{};
;     const char* kb[4];
; #pragma unroll
;     for (int dd = 0; dd < 4; ++dd) kb[dd] = K_lds + KB * SHM_K + KSWZ(r32, (dd * 16 + hi * 8) * 2);
; #pragma unroll
;     for (int d0 = 0; d0 < 8; ++d0) { const char* a = kb[d0 & 3] + (d0 >> 2) * 128;
;         bf16x8 b0 = *reinterpret_cast<const bf16x8*>(a);
;         bf16x8 b1 = *reinterpret_cast<const bf16x8*>(a + 32 * 256);
;         p0 = __builtin_amdgcn_mfma_f32_32x32x16_bf16(b0, qr[d0], p0, 0, 0, 0);
;         p1 = __builtin_amdgcn_mfma_f32_32x32x16_bf16(b1, qr[d0], p1, 0, 0, 0); }
; __device__ __forceinline__ void attn_block(const BlockRef& cur, const BlockRef& nxt, char* lds, Seam& S) {
;     ...
;     SWRITE_HV(0); SBAR();
;     mw = LDMASK(0);
;     if (NT > 1) { SLOAD_H(Kh, Vh, KBASE(1)); }
;     SBAR(); qkt<0>(pA0, pA1, K_lds, r32, hi, S.qr);
;     MASKT(pA0, pA1); partialSM(pA0, pA1, m_reg, mnA, alA);
;     if (NT > 1) { VMW(); SWRITE_H(1); }
;     __syncthreads();
.LBB0_1298:
	v_readfirstlane_b32 s83, v0
	s_lshr_b32 s12, s38, 6
	s_or_b32 s81, s12, 3
	s_and_b32 s12, s83, 0x3fffffc0
	s_lshl_b32 s12, s12, 2
	s_add_i32 s84, s12, 0
	s_lshr_b32 s12, s83, 1
	s_and_b32 s12, s12, 0x7fffffe0
	v_and_b32_e32 v88, 31, v0
	v_or_b32_e32 v186, s12, v88
	s_mov_b32 s82, 1
	v_lshlrev_b32_e32 v165, 9, v186
	s_add_i32 s84, s84, 0x10000
	s_waitcnt vmcnt(1)
	ds_write_b128 v197, v[130:133]
	s_waitcnt vmcnt(0)
	ds_write_b128 v198, v[134:137]
	v_mov_b32_e32 v183, v167
	v_lshl_add_u64 v[2:3], s[70:71], 0, v[182:183]
	v_mov_b32_e32 v177, v167
	v_mov_b32_e32 v185, v167
	v_lshl_add_u64 v[2:3], v[2:3], 0, v[176:177]
	v_lshl_add_u64 v[4:5], s[70:71], 0, v[184:185]
	global_load_dwordx2 v[86:87], v165, s[68:69]
	v_lshl_add_u64 v[4:5], v[4:5], 0, v[176:177]
	global_load_dwordx4 v[50:53], v[2:3], off
	global_load_dwordx4 v[54:57], v[4:5], off
	v_lshl_add_u64 v[2:3], s[6:7], 0, v[182:183]
	v_lshl_add_u64 v[2:3], v[2:3], 0, v[176:177]
	v_lshl_add_u64 v[4:5], s[6:7], 0, v[184:185]
	v_lshl_add_u64 v[4:5], v[4:5], 0, v[176:177]
	global_load_dwordx4 v[58:61], v[2:3], off
	global_load_dwordx4 v[62:65], v[4:5], off
	ds_read_b128 v[2:5], v199 offset:32768
	ds_read_b128 v[6:9], v199 offset:32896
	s_mov_b32 s36, s13
	s_mov_b32 s37, s13
	s_mov_b32 s38, s13
	s_waitcnt lgkmcnt(1)
	v_mfma_f32_32x32x16_bf16 v[34:49], v[2:5], v[126:129], 0
	ds_read_b128 v[2:5], v199 offset:40960
	ds_read_b128 v[10:13], v199 offset:41088
	s_mov_b32 s39, s13
	s_mov_b32 s40, s13
	s_mov_b32 s41, s13
	s_mov_b32 s42, s13
	s_mov_b32 s43, s13
	s_mov_b32 s44, s13
	s_waitcnt lgkmcnt(1)
	v_mfma_f32_32x32x16_bf16 v[18:33], v[2:5], v[126:129], 0
	ds_read_b128 v[2:5], v200 offset:32768
	ds_read_b128 v[14:17], v200 offset:32896
	s_mov_b32 s45, s13
	s_mov_b32 s46, s13
	s_mov_b32 s47, s13
	s_mov_b32 s48, s13
	s_mov_b32 s49, s13
	s_mov_b32 s50, s13
	s_waitcnt lgkmcnt(1)
	v_mfma_f32_32x32x16_bf16 v[34:49], v[2:5], v[122:125], v[34:49]
	ds_read_b128 v[2:5], v200 offset:40960
	ds_read_b128 v[66:69], v200 offset:41088
	s_mov_b32 s51, s13
	v_lshl_add_u32 v185, v88, 2, s84
	v_lshl_add_u32 v183, v163, 2, s84
	v_add_u32_e32 v188, v170, v252
	s_mov_b64 s[16:17], s[70:71]
	s_mov_b64 s[100:101], s[6:7]
	v_mov_b32_e32 v205, 0
	s_waitcnt lgkmcnt(1)
	v_mfma_f32_32x32x16_bf16 v[18:33], v[2:5], v[122:125], v[18:33]
	ds_read_b128 v[2:5], v201 offset:32768
	ds_read_b128 v[70:73], v201 offset:32896
	s_waitcnt lgkmcnt(1)
	v_mfma_f32_32x32x16_bf16 v[34:49], v[2:5], v[118:121], v[34:49]
	ds_read_b128 v[2:5], v201 offset:40960
	ds_read_b128 v[74:77], v201 offset:41088
	s_waitcnt lgkmcnt(1)
	v_mfma_f32_32x32x16_bf16 v[18:33], v[2:5], v[118:121], v[18:33]
	ds_read_b128 v[2:5], v202 offset:32768
	ds_read_b128 v[78:81], v202 offset:32896
	s_waitcnt lgkmcnt(1)
	v_mfma_f32_32x32x16_bf16 v[34:49], v[2:5], v[114:117], v[34:49]
	ds_read_b128 v[2:5], v202 offset:40960
	ds_read_b128 v[82:85], v202 offset:41088
	s_waitcnt vmcnt(0)
	s_waitcnt vmcnt(3)
	ds_write_b128 v197, v[50:53] offset:16384
	s_waitcnt vmcnt(2)
	ds_write_b128 v198, v[54:57] offset:16384
	s_waitcnt vmcnt(1)
	ds_write_b128 v204, v[58:61] offset:49152
	s_waitcnt vmcnt(0)
	ds_write_b128 v204, v[62:65] offset:57344
	s_waitcnt lgkmcnt(0)
	s_barrier
; __device__ __forceinline__ void sel_mask_tile(f32x16& p0, f32x16& p1, unsigned wlo, unsigned whi, int hi) {
;     const unsigned NEGB = 0xff800000u;
;     const unsigned lo = wlo >> (4 * hi), h2 = whi >> (4 * hi);
; #pragma unroll
;     for (int r = 0; r < 16; ++r) {
;         const int c = (r & 3) + 8 * (r >> 2);
;         const unsigned m0 = (unsigned)__builtin_amdgcn_sbfe((int)lo, c, 1), m1 = (unsigned)__builtin_amdgcn_sbfe((int)h2, c, 1);
;         p0[r] = __uint_as_float((__float_as_uint(p0[r]) & m0) | (NEGB & ~m0));
;         p1[r] = __uint_as_float((__float_as_uint(p1[r]) & m1) | (NEGB & ~m1));
;     }
; }
; __device__ __forceinline__ void partialSM(f32x16& p0, f32x16& p1, float& m_reg, float& mn, float& alpha) {
;     float pmax = p0[0];
; #pragma unroll
;     for (int r = 1; r < 16; ++r) pmax = fmaxf(pmax, p0[r]);
; #pragma unroll
;     for (int r = 0; r < 16; ++r) pmax = fmaxf(pmax, p1[r]);
;     { auto rr = __builtin_amdgcn_permlane32_swap(__float_as_uint(pmax), __float_as_uint(pmax), false, false);
;       pmax = fmaxf(__uint_as_float(rr[0]), __uint_as_float(rr[1])); }
;     constexpr float C2 = 1.4426950408889634f * SCALE;
;     if (__builtin_expect(__all((pmax - m_reg) * SCALE <= THR), 1)) { mn = m_reg; alpha = 1.f; }
;     else { mn = fmaxf(m_reg, pmax); alpha = __builtin_amdgcn_exp2f((m_reg - mn) * C2); m_reg = mn; }
;     const float mnL = -mn * C2;
; #pragma unroll
;     for (int r = 0; r < 16; ++r) p0[r] = fmaf(p0[r], C2, mnL);
; #pragma unroll
;     for (int r = 0; r < 16; ++r) p1[r] = fmaf(p1[r], C2, mnL);
; #pragma unroll
;     for (int r = 0; r < 16; ++r) p0[r] = __builtin_amdgcn_exp2f(p0[r]);
	v_mfma_f32_32x32x16_bf16 v[34:49], v[6:9], v[110:113], v[34:49]
	v_mfma_f32_32x32x16_bf16 v[18:33], v[2:5], v[114:117], v[18:33]
	v_mfma_f32_32x32x16_bf16 v[34:49], v[14:17], v[106:109], v[34:49]
	v_mfma_f32_32x32x16_bf16 v[18:33], v[10:13], v[110:113], v[18:33]
	v_mov_b64_e32 v[2:3], s[36:37]
	v_mov_b64_e32 v[4:5], s[38:39]
	v_mov_b64_e32 v[6:7], s[40:41]
	v_mov_b64_e32 v[8:9], s[42:43]
	v_mov_b64_e32 v[10:11], s[44:45]
	v_mov_b64_e32 v[12:13], s[46:47]
	v_mov_b64_e32 v[14:15], s[48:49]
	v_mfma_f32_32x32x16_bf16 v[34:49], v[70:73], v[102:105], v[34:49]
	v_mov_b64_e32 v[16:17], s[50:51]
	v_mov_b64_e32 v[64:65], v[16:17]
	v_mov_b64_e32 v[62:63], v[14:15]
	v_mov_b64_e32 v[60:61], v[12:13]
	v_mov_b64_e32 v[58:59], v[10:11]
	v_mov_b64_e32 v[56:57], v[8:9]
	v_mov_b64_e32 v[54:55], v[6:7]
	v_mfma_f32_32x32x16_bf16 v[18:33], v[66:69], v[106:109], v[18:33]
	v_lshrrev_b32_e32 v66, v163, v86
	v_bfe_i32 v68, v66, 0, 1
	v_lshrrev_b32_e32 v67, v163, v87
	v_bfe_i32 v69, v67, 0, 1
	v_bfe_i32 v70, v67, 2, 1
	v_bfe_i32 v71, v67, 3, 1
	v_bfe_i32 v72, v67, 8, 1
	v_mfma_f32_32x32x16_bf16 v[34:49], v[78:81], v[98:101], v[34:49]
	v_bfe_i32 v73, v67, 9, 1
	v_bfe_i32 v78, v67, 18, 1
	v_bfe_i32 v79, v67, 19, 1
	v_bfe_i32 v80, v67, 24, 1
	v_bfe_i32 v81, v67, 25, 1
	v_mov_b64_e32 v[52:53], v[4:5]
	v_mov_b64_e32 v[50:51], v[2:3]
	v_mfma_f32_32x32x16_bf16 v[18:33], v[74:77], v[102:105], v[18:33]
	s_nop 3
	v_bitop3_b32 v68, v34, s74, v68 bitop3:0xe4
	v_bfe_i32 v34, v66, 1, 1
	v_bitop3_b32 v35, v35, s74, v34 bitop3:0xe4
	v_bfe_i32 v34, v66, 2, 1
	v_bitop3_b32 v36, v36, s74, v34 bitop3:0xe4
	v_bfe_i32 v34, v66, 3, 1
	v_bitop3_b32 v37, v37, s74, v34 bitop3:0xe4
	v_bfe_i32 v34, v66, 8, 1
	v_bitop3_b32 v38, v38, s74, v34 bitop3:0xe4
	v_bfe_i32 v34, v66, 9, 1
	v_bitop3_b32 v39, v39, s74, v34 bitop3:0xe4
	v_bfe_i32 v34, v66, 10, 1
	v_bitop3_b32 v40, v40, s74, v34 bitop3:0xe4
	v_bfe_i32 v34, v66, 11, 1
	v_mfma_f32_32x32x16_bf16 v[18:33], v[82:85], v[98:101], v[18:33]
	v_bitop3_b32 v41, v41, s74, v34 bitop3:0xe4
	v_bfe_i32 v34, v66, 16, 1
	v_bitop3_b32 v42, v42, s74, v34 bitop3:0xe4
	v_bfe_i32 v34, v66, 17, 1
	v_bitop3_b32 v43, v43, s74, v34 bitop3:0xe4
	v_bfe_i32 v34, v66, 18, 1
	v_bitop3_b32 v44, v44, s74, v34 bitop3:0xe4
	v_bfe_i32 v34, v66, 19, 1
	v_bitop3_b32 v45, v45, s74, v34 bitop3:0xe4
	v_bfe_i32 v34, v66, 24, 1
	v_bitop3_b32 v46, v46, s74, v34 bitop3:0xe4
	v_bfe_i32 v34, v66, 25, 1
	v_bitop3_b32 v47, v47, s74, v34 bitop3:0xe4
	v_bfe_i32 v34, v66, 26, 1
	v_bitop3_b32 v48, v48, s74, v34 bitop3:0xe4
	v_bfe_i32 v34, v66, 27, 1
	v_bitop3_b32 v18, v18, s74, v69 bitop3:0xe4
	v_bfe_i32 v69, v67, 1, 1
	v_bfe_i32 v74, v67, 10, 1
	v_bfe_i32 v75, v67, 11, 1
	v_bfe_i32 v76, v67, 16, 1
	v_bfe_i32 v77, v67, 17, 1
	v_bfe_i32 v82, v67, 26, 1
	v_bfe_i32 v66, v67, 27, 1
	v_bitop3_b32 v49, v49, s74, v34 bitop3:0xe4
	v_max_f32_e32 v34, v35, v35
	v_max_f32_e32 v67, v68, v68
	v_max_f32_e32 v34, v67, v34
	v_max3_f32 v34, v34, v36, v37
	v_max3_f32 v34, v34, v38, v39
	v_max3_f32 v34, v34, v40, v41
	v_max3_f32 v34, v34, v42, v43
	v_max3_f32 v34, v34, v44, v45
	v_max3_f32 v34, v34, v46, v47
	v_max3_f32 v34, v34, v48, v49
	v_bitop3_b32 v19, v19, s74, v69 bitop3:0xe4
	v_bitop3_b32 v20, v20, s74, v70 bitop3:0xe4
	v_max3_f32 v34, v34, v18, v19
	v_bitop3_b32 v21, v21, s74, v71 bitop3:0xe4
	v_bitop3_b32 v22, v22, s74, v72 bitop3:0xe4
	v_max3_f32 v34, v34, v20, v21
	v_bitop3_b32 v23, v23, s74, v73 bitop3:0xe4
	v_bitop3_b32 v24, v24, s74, v74 bitop3:0xe4
	v_max3_f32 v34, v34, v22, v23
	v_bitop3_b32 v25, v25, s74, v75 bitop3:0xe4
	v_bitop3_b32 v26, v26, s74, v76 bitop3:0xe4
	v_max3_f32 v34, v34, v24, v25
	v_bitop3_b32 v27, v27, s74, v77 bitop3:0xe4
	v_bitop3_b32 v28, v28, s74, v78 bitop3:0xe4
	v_max3_f32 v34, v34, v26, v27
	v_bitop3_b32 v29, v29, s74, v79 bitop3:0xe4
	v_bitop3_b32 v30, v30, s74, v80 bitop3:0xe4
	v_max3_f32 v34, v34, v28, v29
	v_bitop3_b32 v31, v31, s74, v81 bitop3:0xe4
	v_bitop3_b32 v32, v32, s74, v82 bitop3:0xe4
	v_max3_f32 v34, v34, v30, v31
	v_bitop3_b32 v33, v33, s74, v66 bitop3:0xe4
	v_max3_f32 v34, v34, v32, v33
	v_mov_b32_e32 v66, v34
	s_nop 1
	v_permlane32_swap_b32_e32 v34, v66
	v_max_f32_e32 v66, v66, v66
	v_max_f32_e32 v34, v34, v34
	v_max_f32_e32 v34, v34, v66
	v_add_f32_e32 v66, 0x7149f2ca, v34
	v_mul_f32_e32 v66, 0x3db504f3, v66
	v_max_f32_e32 v34, 0xf149f2ca, v34
	v_cmp_ge_f32_e32 vcc, s75, v66
	v_sub_f32_e32 v66, 0xf149f2ca, v34
	v_mul_f32_e32 v66, 0x3e0293ee, v66
	s_cmp_eq_u64 vcc, exec
	v_exp_f32_e32 v66, v66
	s_cselect_b64 vcc, -1, 0
	v_cndmask_b32_e32 v206, v34, v203, vcc
	v_mul_f32_e32 v34, 0xbe0293ee, v206
	v_mov_b32_e32 v67, v34
	v_cndmask_b32_e64 v177, v66, 1.0, vcc
	v_fmamk_f32 v66, v68, 0x3e0293ee, v34
	v_fmamk_f32 v35, v35, 0x3e0293ee, v34
	v_fmamk_f32 v36, v36, 0x3e0293ee, v34
	v_fmamk_f32 v37, v37, 0x3e0293ee, v34
	v_fmamk_f32 v38, v38, 0x3e0293ee, v34
	v_fmamk_f32 v39, v39, 0x3e0293ee, v34
	v_fmamk_f32 v40, v40, 0x3e0293ee, v34
	v_fmamk_f32 v41, v41, 0x3e0293ee, v34
	v_fmamk_f32 v42, v42, 0x3e0293ee, v34
	v_fmamk_f32 v43, v43, 0x3e0293ee, v34
	v_fmamk_f32 v44, v44, 0x3e0293ee, v34
	v_fmamk_f32 v45, v45, 0x3e0293ee, v34
	v_fmamk_f32 v46, v46, 0x3e0293ee, v34
	v_fmamk_f32 v47, v47, 0x3e0293ee, v34
	v_fmamk_f32 v48, v48, 0x3e0293ee, v34
	v_fmac_f32_e32 v67, 0x3e0293ee, v49
	v_exp_f32_e32 v219, v66
	v_exp_f32_e32 v220, v35
	v_exp_f32_e32 v221, v36
	v_exp_f32_e32 v222, v37
	v_exp_f32_e32 v223, v38
	v_exp_f32_e32 v225, v39
	v_exp_f32_e32 v224, v40
	v_exp_f32_e32 v226, v41
	v_exp_f32_e32 v211, v42
	v_exp_f32_e32 v212, v43
	v_exp_f32_e32 v213, v44
	v_exp_f32_e32 v215, v45
	v_exp_f32_e32 v214, v46
	v_exp_f32_e32 v216, v47
	v_exp_f32_e32 v217, v48
	v_exp_f32_e32 v218, v67
	s_lshl_b32 s36, s83, 8
	v_pk_fma_f32 v[152:153], v[32:33], s[14:15], v[34:35] op_sel_hi:[1,0,0]
	v_pk_fma_f32 v[156:157], v[30:31], s[14:15], v[34:35] op_sel_hi:[1,0,0]
	v_pk_fma_f32 v[160:161], v[28:29], s[14:15], v[34:35] op_sel_hi:[1,0,0]
	v_pk_fma_f32 v[150:151], v[26:27], s[14:15], v[34:35] op_sel_hi:[1,0,0]
	v_pk_fma_f32 v[154:155], v[24:25], s[14:15], v[34:35] op_sel_hi:[1,0,0]
	v_pk_fma_f32 v[158:159], v[22:23], s[14:15], v[34:35] op_sel_hi:[1,0,0]
	v_pk_fma_f32 v[192:193], v[20:21], s[14:15], v[34:35] op_sel_hi:[1,0,0]
	v_pk_fma_f32 v[194:195], v[18:19], s[14:15], v[34:35] op_sel_hi:[1,0,0]
	s_and_b32 s36, s36, 0xffffc000
	v_mov_b64_e32 v[48:49], v[16:17]
	v_mov_b64_e32 v[32:33], v[16:17]
	v_or_b32_e32 v179, s36, v254
	v_mov_b64_e32 v[46:47], v[14:15]
	v_mov_b64_e32 v[44:45], v[12:13]
	v_mov_b64_e32 v[42:43], v[10:11]
	v_mov_b64_e32 v[40:41], v[8:9]
	v_mov_b64_e32 v[38:39], v[6:7]
	v_mov_b64_e32 v[36:37], v[4:5]
	v_mov_b64_e32 v[34:35], v[2:3]
	v_mov_b64_e32 v[30:31], v[14:15]
	v_mov_b64_e32 v[28:29], v[12:13]
	v_mov_b64_e32 v[26:27], v[10:11]
	v_mov_b64_e32 v[24:25], v[8:9]
	v_mov_b64_e32 v[22:23], v[6:7]
	v_mov_b64_e32 v[20:21], v[4:5]
	v_mov_b64_e32 v[18:19], v[2:3]
	v_mul_f32_e32 v190, 0xbe0293ee, v206
	s_nop 0
	s_mov_b32 s76, 0
	v_readfirstlane_b32 s77, v0
	s_nop 3
	s_lshr_b32 s77, s77, 8
	s_cmp_eq_u32 s77, 0
	s_cbranch_scc1 .Lp5_lead
	s_barrier
